# attention V tile in LDS: 64-byte rows with 8-byte-chunk XOR swizzle instead of 80-byte padded rows (transposed 2-byte writes were 16-way bank conflicted)
# speedup vs baseline: 1.0267x; 1.0001x over previous
.LBB0_435:
	s_or_b64 exec, exec, s[0:1]
	s_mov_b64 s[0:1], src_shared_base
	s_add_i32 s0, 0, 0x11fe0
	s_cmp_lg_u32 s0, -1
	s_cselect_b32 s0, s0, 0
	s_cselect_b32 s1, s1, 0
	v_mov_b32_e32 v0, s0
	v_mov_b32_e32 v1, s1
	s_waitcnt lgkmcnt(0)
	s_barrier
	s_waitcnt vmcnt(11)
	flat_load_dword v32, v[0:1] sc0 sc1
	s_waitcnt vmcnt(0)
	v_readlane_b32 s0, v254, 54
	s_waitcnt lgkmcnt(0)
	s_nop 0
	v_cmp_gt_i32_e32 vcc, s0, v32
	s_mov_b64 s[0:1], -1
	s_and_saveexec_b64 s[96:97], vcc
	s_cbranch_execz .LBB0_430
	s_movk_i32 s0, 0x600
	v_cmp_gt_i32_e32 vcc, s0, v32
	s_and_saveexec_b64 s[0:1], vcc
	s_xor_b64 s[0:1], exec, s[0:1]
	v_writelane_b32 v255, s0, 2
	s_nop 1
	v_writelane_b32 v255, s1, 3
	s_cbranch_execz .LBB0_560
	s_movk_i32 s0, 0x500
	v_cmp_gt_i32_e32 vcc, s0, v32
	s_and_saveexec_b64 s[0:1], vcc
	s_xor_b64 s[0:1], exec, s[0:1]
	v_writelane_b32 v255, s0, 4
	s_nop 1
	v_writelane_b32 v255, s1, 5
	s_cbranch_execz .LBB0_551
	s_movk_i32 s0, 0x7f
	v_cmp_lt_i32_e32 vcc, s0, v32
	s_and_saveexec_b64 s[0:1], vcc
	s_xor_b64 s[0:1], exec, s[0:1]
	s_cbranch_execz .LBB0_526
	v_writelane_b32 v255, s0, 6
	v_cmp_lt_u32_e32 vcc, s89, v32
	s_nop 0
	v_writelane_b32 v255, s1, 7
	s_and_saveexec_b64 s[0:1], vcc
	s_xor_b64 s[16:17], exec, s[0:1]
	s_cbranch_execz .LBB0_507
	s_movk_i32 s0, 0x2ff
	v_cmp_lt_u32_e32 vcc, s0, v32
	s_and_saveexec_b64 s[0:1], vcc
	s_xor_b64 s[0:1], exec, s[0:1]
	s_cbranch_execz .LBB0_448
	v_add_u32_e32 v0, 0xfffffd00, v32
	v_mov_b32_e32 v35, v166
	v_lshrrev_b32_e32 v33, 4, v0
	v_bfe_u32 v34, v32, 3, 1
	v_lshlrev_b32_e32 v69, 8, v33
	v_ashrrev_i32_e32 v0, 6, v35
	v_lshl_add_u32 v36, v34, 2, v0
	v_lshlrev_b32_e32 v0, 5, v32
	v_and_b32_e32 v68, 15, v35
	v_and_b32_e32 v70, 0xe0, v0
	v_lshlrev_b32_e32 v48, 6, v36
	v_ashrrev_i32_e32 v49, 31, v48
	v_or3_b32 v2, v70, v68, v69
	v_bfe_u32 v53, v35, 4, 2
	v_lshl_add_u64 v[0:1], v[48:49], 2, s[30:31]
	v_lshlrev_b32_e32 v128, 13, v2
	v_lshl_add_u64 v[16:17], v[0:1], 0, v[128:129]
	v_lshlrev_b32_e32 v128, 5, v53
	s_mov_b64 s[2:3], 0x20000
	v_lshl_add_u64 v[12:13], v[16:17], 0, v[128:129]
	v_lshl_add_u64 v[24:25], v[16:17], 0, s[2:3]
	global_load_dwordx4 v[0:3], v[12:13], off
	global_load_dwordx4 v[4:7], v[12:13], off offset:16
	global_load_dwordx4 v[8:11], v[12:13], off offset:128
	s_nop 0
	global_load_dwordx4 v[12:15], v[12:13], off offset:144
	v_lshl_add_u64 v[20:21], v[24:25], 0, v[128:129]
	global_load_dwordx4 v[16:19], v[20:21], off
	s_nop 0
	global_load_dwordx4 v[20:23], v[20:21], off offset:16
	v_or_b32_e32 v128, 0x80, v128
	v_lshl_add_u64 v[28:29], v[24:25], 0, v[128:129]
	global_load_dwordx4 v[24:27], v[28:29], off
	s_nop 0
	global_load_dwordx4 v[28:31], v[28:29], off offset:16
	s_mov_b32 s2, 0x3e000000
	v_readlane_b32 s68, v254, 8
	v_readlane_b32 s69, v254, 9
	v_ashrrev_i32_e32 v73, 3, v35
	v_and_b32_e32 v58, 7, v35
	v_lshlrev_b32_e32 v128, 8, v34
	v_cmp_eq_u32_e32 vcc, 0, v53
	v_lshrrev_b32_e32 v32, 4, v35
	v_lshl_add_u32 v59, v53, 3, 0
	v_mul_u32_u24_e32 v67, 0x50, v68
	s_mov_b32 s24, 0
	v_add_u32_e32 v79, v59, v67
	v_bfe_u32 v79, v166, 4, 2
	v_bfe_u32 v67, v166, 3, 1
	v_xor_b32_e32 v79, v79, v67
	v_lshlrev_b32_e32 v79, 3, v79
	v_and_b32_e32 v67, 15, v166
	v_lshl_or_b32 v79, v67, 6, v79
	v_readlane_b32 s70, v254, 10
	v_readlane_b32 s71, v254, 11
	v_readlane_b32 s72, v254, 12
	v_readlane_b32 s73, v254, 13
	v_readlane_b32 s74, v254, 14
	v_readlane_b32 s75, v254, 15
	v_readlane_b32 s76, v254, 16
	v_readlane_b32 s77, v254, 17
	v_readlane_b32 s78, v254, 18
	v_readlane_b32 s79, v254, 19
	v_readlane_b32 s80, v254, 20
	v_readlane_b32 s81, v254, 21
	v_readlane_b32 s82, v254, 22
	v_readlane_b32 s83, v254, 23
	s_waitcnt vmcnt(7)
	v_pk_mul_f32 v[0:1], v[0:1], s[2:3] op_sel_hi:[1,0]
	v_pk_mul_f32 v[2:3], v[2:3], s[2:3] op_sel_hi:[1,0]
	s_waitcnt vmcnt(6)
	v_pk_mul_f32 v[4:5], v[4:5], s[2:3] op_sel_hi:[1,0]
	v_pk_mul_f32 v[6:7], v[6:7], s[2:3] op_sel_hi:[1,0]
	s_waitcnt vmcnt(5)
	v_pk_mul_f32 v[8:9], v[8:9], s[2:3] op_sel_hi:[1,0]
	v_pk_mul_f32 v[10:11], v[10:11], s[2:3] op_sel_hi:[1,0]
	s_waitcnt vmcnt(4)
	v_pk_mul_f32 v[14:15], v[14:15], s[2:3] op_sel_hi:[1,0]
	v_pk_mul_f32 v[12:13], v[12:13], s[2:3] op_sel_hi:[1,0]
	v_bfe_u32 v37, v7, 16, 1
	v_bfe_u32 v39, v3, 16, 1
	v_bfe_u32 v41, v5, 16, 1
	v_bfe_u32 v42, v4, 16, 1
	v_bfe_u32 v43, v1, 16, 1
	v_bfe_u32 v44, v0, 16, 1
	v_bfe_u32 v45, v15, 16, 1
	v_bfe_u32 v46, v14, 16, 1
	v_bfe_u32 v47, v11, 16, 1
	v_bfe_u32 v50, v10, 16, 1
	v_bfe_u32 v54, v9, 16, 1
	v_bfe_u32 v55, v8, 16, 1
	s_waitcnt vmcnt(3)
	v_pk_mul_f32 v[16:17], v[16:17], s[2:3] op_sel_hi:[1,0]
	s_waitcnt vmcnt(2)
	v_pk_mul_f32 v[20:21], v[20:21], s[2:3] op_sel_hi:[1,0]
	v_bfe_u32 v51, v13, 16, 1
	v_bfe_u32 v52, v12, 16, 1
	v_add3_u32 v3, v3, v39, s56
	v_add3_u32 v7, v7, v37, s56
	v_add3_u32 v37, v0, v44, s56
	v_add3_u32 v1, v1, v43, s56
	v_add3_u32 v39, v4, v42, s56
	v_add3_u32 v5, v5, v41, s56
	v_add3_u32 v41, v10, v50, s56
	v_add3_u32 v42, v11, v47, s56
	v_add3_u32 v43, v14, v46, s56
	v_add3_u32 v44, v15, v45, s56
	v_add3_u32 v45, v8, v55, s56
	v_add3_u32 v46, v9, v54, s56
	v_bfe_u32 v8, v21, 16, 1
	v_bfe_u32 v9, v20, 16, 1
	v_bfe_u32 v10, v17, 16, 1
	v_bfe_u32 v11, v16, 16, 1
	v_pk_mul_f32 v[18:19], v[18:19], s[2:3] op_sel_hi:[1,0]
	v_pk_mul_f32 v[22:23], v[22:23], s[2:3] op_sel_hi:[1,0]
	v_add3_u32 v47, v12, v52, s56
	v_add3_u32 v51, v13, v51, s56
	v_add3_u32 v56, v16, v11, s56
	v_add3_u32 v57, v17, v10, s56
	v_add3_u32 v20, v20, v9, s56
	v_add3_u32 v21, v21, v8, s56
	s_waitcnt vmcnt(1)
	v_pk_mul_f32 v[8:9], v[24:25], s[2:3] op_sel_hi:[1,0]
	v_pk_mul_f32 v[10:11], v[26:27], s[2:3] op_sel_hi:[1,0]
	s_waitcnt vmcnt(0)
	v_pk_mul_f32 v[12:13], v[28:29], s[2:3] op_sel_hi:[1,0]
	v_pk_mul_f32 v[14:15], v[30:31], s[2:3] op_sel_hi:[1,0]
	v_readlane_b32 s2, v254, 56
	v_bfe_u32 v24, v15, 16, 1
	v_bfe_u32 v29, v8, 16, 1
	v_add_u32_e32 v16, s2, v36
	v_ashrrev_i32_e32 v17, 31, v16
	v_lshl_add_u64 v[16:17], v[16:17], 2, s[68:69]
	global_load_dword v81, v[16:17], off
	v_bfe_u32 v25, v14, 16, 1
	v_bfe_u32 v28, v9, 16, 1
	v_add3_u32 v15, v15, v24, s56
	v_add3_u32 v24, v8, v29, s56
	v_add_u32_e32 v8, v73, v69
	v_add3_u32 v14, v14, v25, s56
	v_add3_u32 v25, v9, v28, s56
	v_ashrrev_i32_e32 v9, 31, v8
	v_mbcnt_lo_u32_b32 v28, -1, 0
	v_bfe_u32 v40, v2, 16, 1
	v_lshlrev_b64 v[8:9], 13, v[8:9]
	v_mbcnt_hi_u32_b32 v28, -1, v28
	v_bfe_u32 v38, v6, 16, 1
	v_add3_u32 v40, v2, v40, s56
	v_bfe_u32 v2, v22, 16, 1
	v_bfe_u32 v4, v19, 16, 1
	v_lshl_add_u64 v[8:9], s[30:31], 0, v[8:9]
	v_and_b32_e32 v30, 64, v28
	v_add3_u32 v38, v6, v38, s56
	v_bfe_u32 v6, v18, 16, 1
	v_add3_u32 v19, v19, v4, s56
	v_add3_u32 v22, v22, v2, s56
	v_lshlrev_b32_e32 v2, 2, v35
	v_lshlrev_b32_e32 v4, 3, v58
	v_lshl_add_u64 v[8:9], v[8:9], 0, v[128:129]
	s_mov_b64 s[2:3], 0xa00
	v_xor_b32_e32 v29, 16, v28
	v_add_u32_e32 v30, 64, v30
	v_add3_u32 v18, v18, v6, s56
	v_cndmask_b32_e64 v50, 0, 1.0, vcc
	v_and_b32_e32 v2, 12, v2
	v_and_b32_e32 v6, 32, v4
	v_lshl_add_u64 v[64:65], v[8:9], 0, s[2:3]
	s_mov_b64 s[2:3], 0x800
	v_cmp_lt_i32_e32 vcc, v29, v30
	v_lshl_add_u64 v[62:63], v[8:9], 0, s[2:3]
	v_or_b32_e32 v9, v6, v2
	v_cndmask_b32_e32 v29, v28, v29, vcc
	v_bfe_u32 v16, v13, 16, 1
	v_bfe_u32 v17, v12, 16, 1
	v_bfe_u32 v8, v35, 4, 3
	v_lshrrev_b32_e32 v9, 3, v9
	v_lshlrev_b32_e32 v72, 2, v29
	v_xor_b32_e32 v29, 32, v28
	v_add3_u32 v12, v12, v17, s56
	v_add3_u32 v13, v13, v16, s56
	v_lshl_add_u32 v16, v73, 7, 0
	v_bitop3_b32 v17, v9, v32, 7 bitop3:0x78
	v_bitop3_b32 v8, v9, v8, 2 bitop3:0x36
	v_cmp_lt_i32_e32 vcc, v29, v30
	v_bfe_u32 v26, v11, 16, 1
	v_lshl_add_u32 v17, v17, 4, v16
	v_lshl_add_u32 v8, v8, 4, v16
	v_readlane_b32 s2, v254, 63
	v_bfe_u32 v16, v35, 1, 3
	v_cndmask_b32_e32 v28, v28, v29, vcc
	v_bfe_u32 v0, v23, 16, 1
	v_bfe_u32 v27, v10, 16, 1
	v_add3_u32 v11, v11, v26, s56
	v_lshlrev_b32_e32 v26, 3, v35
	v_lshl_or_b32 v54, v33, 9, s2
	v_lshlrev_b32_e32 v71, 2, v28
	s_movk_i32 s2, 0x280
	v_bitop3_b32 v28, v32, v16, 3 bitop3:0x6c
	v_bitop3_b32 v16, v53, v16, 4 bitop3:0x36
	v_add3_u32 v23, v23, v0, s56
	v_mov_b32_e32 v0, 0
	v_add3_u32 v10, v10, v27, s56
	v_and_b32_e32 v26, 8, v26
	v_lshlrev_b32_e32 v9, 1, v73
	v_lshl_add_u32 v27, v68, 7, 0
	v_mad_u32_u24 v61, v58, s2, 0
	v_lshlrev_b32_e32 v66, 4, v28
	v_lshlrev_b32_e32 v16, 4, v16
	s_mov_b32 s2, 0x7060302
	v_lshlrev_b32_e32 v52, 6, v34
	v_mov_b32_e32 v55, v129
	v_perm_b32 v31, v7, v38, s2
	v_perm_b32 v29, v3, v40, s2
	v_perm_b32 v30, v5, v39, s2
	v_perm_b32 v28, v1, v37, s2
	v_perm_b32 v35, v44, v43, s2
	v_perm_b32 v33, v42, v41, s2
	v_perm_b32 v34, v51, v47, s2
	v_perm_b32 v32, v46, v45, s2
	v_perm_b32 v39, v23, v22, s2
	v_perm_b32 v37, v19, v18, s2
	v_perm_b32 v38, v21, v20, s2
	v_perm_b32 v36, v57, v56, s2
	v_perm_b32 v47, v15, v14, s2
	v_perm_b32 v45, v11, v10, s2
	v_perm_b32 v46, v13, v12, s2
	v_perm_b32 v44, v25, v24, s2
	v_lshl_add_u64 v[56:57], s[30:31], 0, v[128:129]
	v_lshlrev_b32_e32 v128, 2, v4
	v_lshlrev_b32_e32 v58, 2, v6
	v_lshlrev_b32_e32 v60, 2, v2
	v_add_u32_e32 v74, v17, v26
	v_add_u32_e32 v75, v8, v26
	v_add_u32_e32 v76, v61, v9
	v_and_b32_e32 v76, 7, v166
	v_lshlrev_b32_e32 v76, 9, v76
	v_lshrrev_b32_e32 v77, 5, v166
	v_xor_b32_e32 v77, v77, v166
	v_and_b32_e32 v77, 7, v77
	v_lshl_or_b32 v76, v77, 3, v76
	v_bfe_u32 v77, v166, 3, 2
	v_lshl_or_b32 v76, v77, 1, v76
	v_add_u32_e32 v77, v27, v66
	v_add_u32_e32 v78, v27, v16
	s_waitcnt vmcnt(0)
	v_mov_b32_e32 v80, v81
	v_mov_b32_e32 v1, v0
	v_mov_b32_e32 v2, v0
	v_mov_b32_e32 v3, v0
	v_mov_b32_e32 v4, v0
	v_mov_b32_e32 v5, v0
	v_mov_b32_e32 v6, v0
	v_mov_b32_e32 v7, v0
	v_mov_b32_e32 v8, v0
	v_mov_b32_e32 v9, v0
	v_mov_b32_e32 v10, v0
	v_mov_b32_e32 v11, v0
	v_mov_b32_e32 v12, v0
	v_mov_b32_e32 v13, v0
	v_mov_b32_e32 v14, v0
	v_mov_b32_e32 v15, v0
	v_mov_b32_e32 v16, v0
	v_mov_b32_e32 v17, v0
	v_mov_b32_e32 v18, v0
	v_mov_b32_e32 v19, v0
	v_mov_b32_e32 v20, v0
	v_mov_b32_e32 v21, v0
	v_mov_b32_e32 v22, v0
	v_mov_b32_e32 v23, v0
	v_mov_b32_e32 v24, v0
	v_mov_b32_e32 v25, v0
	v_mov_b32_e32 v26, v0
	v_mov_b32_e32 v27, v0
	v_mov_b32_e32 v40, v0
	v_mov_b32_e32 v41, v0
	v_mov_b32_e32 v42, v0
	v_mov_b32_e32 v43, v0
	v_mov_b32_e32 v51, v50
	s_branch .LBB0_443
.LBB0_442:
	ds_read_b128 v[82:85], v77
	ds_read_b128 v[86:89], v77 offset:2048
	ds_read_b128 v[94:97], v78
	ds_read_b128 v[102:105], v78 offset:2048
	s_mov_b32 s2, 0x7060302
	s_waitcnt lgkmcnt(3)
	v_mfma_f32_16x16x32_bf16 v[90:93], v[82:85], v[28:31], 0
	s_cmp_lg_u32 s24, 8
	s_waitcnt lgkmcnt(2)
	v_mfma_f32_16x16x32_bf16 v[98:101], v[86:89], v[28:31], 0
	s_waitcnt lgkmcnt(1)
	v_mfma_f32_16x16x32_bf16 v[90:93], v[94:97], v[32:35], v[90:93]
	s_waitcnt lgkmcnt(0)
	v_mfma_f32_16x16x32_bf16 v[98:101], v[102:105], v[32:35], v[98:101]
	v_mfma_f32_16x16x32_bf16 v[82:85], v[82:85], v[36:39], 0
	s_nop 4
	v_max_f32_e32 v59, v91, v91
	v_max_f32_e32 v61, v90, v90
	v_max_f32_e32 v66, v93, v93
	v_max_f32_e32 v67, v92, v92
	v_max_f32_e32 v106, v101, v101
	v_max_f32_e32 v107, v100, v100
	v_max_f32_e32 v59, v61, v59
	v_max_f32_e32 v61, v67, v66
	v_max_f32_e32 v66, v107, v106
	v_max3_f32 v66, v98, v99, v66
	v_max3_f32 v59, v59, v61, v66
	ds_bpermute_b32 v61, v72, v59
	v_mfma_f32_16x16x32_bf16 v[86:89], v[86:89], v[36:39], 0
	v_add_u32_e32 v67, 0x1000, v79
	ds_read2_b64 v[106:109], v67 offset1:4
	s_waitcnt lgkmcnt(1)
	v_max_f32_e32 v61, v61, v61
	v_max_f32_e32 v59, v59, v61
	ds_bpermute_b32 v61, v71, v59
	v_mfma_f32_16x16x32_bf16 v[82:85], v[94:97], v[44:47], v[82:85]
	s_waitcnt lgkmcnt(0)
	v_max3_f32 v59, v81, v59, v61
	v_sub_f32_e32 v61, v81, v59
	v_sub_f32_e32 v81, v91, v59
	v_mul_f32_e32 v81, 0x3fb8aa3b, v81
	v_exp_f32_e32 v110, v81
	v_sub_f32_e32 v81, v93, v59
	v_mul_f32_e32 v81, 0x3fb8aa3b, v81
	v_exp_f32_e32 v114, v81
	v_sub_f32_e32 v81, v98, v59
	v_mul_f32_e32 v81, 0x3fb8aa3b, v81
	v_exp_f32_e32 v116, v81
	v_sub_f32_e32 v81, v99, v59
	v_mul_f32_e32 v81, 0x3fb8aa3b, v81
	v_exp_f32_e32 v118, v81
	v_sub_f32_e32 v81, v101, v59
	v_mul_f32_e32 v81, 0x3fb8aa3b, v81
	v_sub_f32_e32 v66, v90, v59
	v_sub_f32_e32 v90, v92, v59
	v_exp_f32_e32 v120, v81
	v_sub_f32_e32 v81, v100, v59
	v_mul_f32_e32 v66, 0x3fb8aa3b, v66
	v_mul_f32_e32 v90, 0x3fb8aa3b, v90
	v_mul_f32_e32 v81, 0x3fb8aa3b, v81
	v_exp_f32_e32 v66, v66
	v_exp_f32_e32 v112, v90
	v_exp_f32_e32 v122, v81
	v_bfe_u32 v81, v120, 16, 1
	v_bfe_u32 v90, v118, 16, 1
	v_bfe_u32 v91, v114, 16, 1
	v_bfe_u32 v92, v110, 16, 1
	v_bfe_u32 v93, v122, 16, 1
	v_bfe_u32 v98, v116, 16, 1
	v_bfe_u32 v99, v112, 16, 1
	v_bfe_u32 v100, v66, 16, 1
	v_mfma_f32_16x16x32_bf16 v[86:89], v[102:105], v[44:47], v[86:89]
	v_add3_u32 v101, v110, v92, s56
	v_add3_u32 v91, v114, v91, s56
	v_add3_u32 v90, v118, v90, s56
	v_add3_u32 v81, v120, v81, s56
	v_add3_u32 v100, v66, v100, s56
	v_add3_u32 v99, v112, v99, s56
	v_add3_u32 v92, v116, v98, s56
	v_add3_u32 v93, v122, v93, s56
	v_perm_b32 v93, v81, v93, s2
	v_perm_b32 v92, v90, v92, s2
	v_perm_b32 v91, v91, v99, s2
	v_perm_b32 v90, v101, v100, s2
	v_xor_b32_e32 v98, 16, v67
	ds_read2_b64 v[98:101], v98 offset0:128 offset1:132
	v_max_f32_e32 v67, v83, v83
	v_max_f32_e32 v81, v82, v82
	v_max_f32_e32 v67, v81, v67
	v_max_f32_e32 v81, v85, v85
	v_max_f32_e32 v102, v84, v84
	v_max_f32_e32 v81, v102, v81
	v_max_f32_e32 v102, v89, v89
	v_max_f32_e32 v103, v88, v88
	v_max_f32_e32 v102, v103, v102
	v_max3_f32 v102, v86, v87, v102
	v_max3_f32 v67, v67, v81, v102
	ds_bpermute_b32 v81, v72, v67
	v_mul_f32_e32 v61, 0x3fb8aa3b, v61
	v_exp_f32_e32 v124, v61
	v_add_u32_e32 v61, 0x1800, v79
	ds_read2_b64 v[94:97], v61 offset0:4 offset1:0
	v_xor_b32_e32 v102, 16, v61
	ds_read2_b64 v[102:105], v102 offset0:132 offset1:128
	s_waitcnt lgkmcnt(2)
	v_max_f32_e32 v61, v81, v81
	v_max_f32_e32 v61, v67, v61
	ds_bpermute_b32 v67, v71, v61
	v_pk_mul_f32 v[42:43], v[42:43], v[124:125] op_sel_hi:[1,0]
	v_pk_mul_f32 v[40:41], v[40:41], v[124:125] op_sel_hi:[1,0]
	v_pk_mul_f32 v[26:27], v[26:27], v[124:125] op_sel_hi:[1,0]
	v_pk_mul_f32 v[24:25], v[24:25], v[124:125] op_sel_hi:[1,0]
	s_waitcnt lgkmcnt(0)
	v_max3_f32 v61, v80, v61, v67
	v_sub_f32_e32 v81, v83, v61
	v_mul_f32_e32 v81, 0x3fb8aa3b, v81
	v_exp_f32_e32 v111, v81
	v_sub_f32_e32 v81, v84, v61
	v_sub_f32_e32 v67, v80, v61
	v_mul_f32_e32 v81, 0x3fb8aa3b, v81
	v_mul_f32_e32 v80, 0x3fb8aa3b, v67
	v_sub_f32_e32 v67, v82, v61
	v_exp_f32_e32 v113, v81
	v_sub_f32_e32 v81, v85, v61
	v_mul_f32_e32 v67, 0x3fb8aa3b, v67
	v_mul_f32_e32 v81, 0x3fb8aa3b, v81
	v_exp_f32_e32 v67, v67
	v_exp_f32_e32 v115, v81
	v_sub_f32_e32 v81, v86, v61
	v_sub_f32_e32 v82, v87, v61
	v_sub_f32_e32 v83, v88, v61
	v_sub_f32_e32 v84, v89, v61
	v_mul_f32_e32 v81, 0x3fb8aa3b, v81
	v_mul_f32_e32 v82, 0x3fb8aa3b, v82
	v_mul_f32_e32 v83, 0x3fb8aa3b, v83
	v_mul_f32_e32 v84, 0x3fb8aa3b, v84
	v_exp_f32_e32 v121, v84
	v_exp_f32_e32 v123, v83
	v_exp_f32_e32 v119, v82
	v_exp_f32_e32 v117, v81
	v_pk_mul_f32 v[22:23], v[22:23], v[124:125] op_sel_hi:[1,0]
	v_pk_mul_f32 v[20:21], v[20:21], v[124:125] op_sel_hi:[1,0]
	v_pk_mul_f32 v[18:19], v[18:19], v[124:125] op_sel_hi:[1,0]
	v_pk_mul_f32 v[16:17], v[16:17], v[124:125] op_sel_hi:[1,0]
	v_bfe_u32 v88, v67, 16, 1
	v_exp_f32_e32 v125, v80
	v_add3_u32 v88, v67, v88, s56
	v_pk_add_f32 v[66:67], v[66:67], 0 op_sel_hi:[1,0]
	v_bfe_u32 v81, v121, 16, 1
	v_bfe_u32 v82, v123, 16, 1
	v_bfe_u32 v83, v119, 16, 1
	v_bfe_u32 v84, v117, 16, 1
	v_pk_add_f32 v[66:67], v[110:111], v[66:67]
	v_bfe_u32 v85, v115, 16, 1
	v_bfe_u32 v86, v113, 16, 1
	v_bfe_u32 v87, v111, 16, 1
	v_add3_u32 v84, v117, v84, s56
	v_add3_u32 v89, v119, v83, s56
	v_add3_u32 v82, v123, v82, s56
	v_add3_u32 v81, v121, v81, s56
	v_pk_add_f32 v[66:67], v[112:113], v[66:67]
	v_add3_u32 v87, v111, v87, s56
	v_add3_u32 v86, v113, v86, s56
	v_add3_u32 v85, v115, v85, s56
	v_pk_add_f32 v[66:67], v[114:115], v[66:67]
	v_perm_b32 v83, v81, v82, s2
	v_perm_b32 v82, v89, v84, s2
	v_mov_b32_e32 v84, v125
	v_pk_add_f32 v[66:67], v[116:117], v[66:67]
	v_perm_b32 v81, v85, v86, s2
	v_perm_b32 v80, v87, v88, s2
	v_pk_mul_f32 v[14:15], v[14:15], v[84:85] op_sel_hi:[1,0]
	v_pk_mul_f32 v[12:13], v[12:13], v[84:85] op_sel_hi:[1,0]
	v_pk_mul_f32 v[10:11], v[10:11], v[84:85] op_sel_hi:[1,0]
	v_pk_mul_f32 v[8:9], v[8:9], v[84:85] op_sel_hi:[1,0]
	v_pk_mul_f32 v[6:7], v[6:7], v[84:85] op_sel_hi:[1,0]
	v_pk_mul_f32 v[4:5], v[4:5], v[84:85] op_sel_hi:[1,0]
	v_pk_mul_f32 v[2:3], v[2:3], v[84:85] op_sel_hi:[1,0]
	v_pk_mul_f32 v[0:1], v[0:1], v[84:85] op_sel_hi:[1,0]
	v_mfma_f32_16x16x32_bf16 v[40:43], v[106:109], v[90:93], v[40:43]
	v_add_f32_e64 v66, v118, v66
	v_add_f32_e64 v67, v119, v67
	v_pk_add_f32 v[66:67], v[122:123], v[66:67]
	v_mfma_f32_16x16x32_bf16 v[24:27], v[98:101], v[90:93], v[24:27]
	v_add_f32_e64 v66, v120, v66
	v_add_f32_e64 v67, v121, v67
	v_pk_fma_f32 v[50:51], v[50:51], v[124:125], v[66:67]
	v_mfma_f32_16x16x32_bf16 v[20:23], v[94:97], v[90:93], v[20:23]
	v_mfma_f32_16x16x32_bf16 v[16:19], v[102:105], v[90:93], v[16:19]
	v_mfma_f32_16x16x32_bf16 v[12:15], v[106:109], v[80:83], v[12:15]
	v_mfma_f32_16x16x32_bf16 v[8:11], v[98:101], v[80:83], v[8:11]
	v_mfma_f32_16x16x32_bf16 v[4:7], v[94:97], v[80:83], v[4:7]
	v_mfma_f32_16x16x32_bf16 v[0:3], v[102:105], v[80:83], v[0:3]
	v_mov_b32_e32 v81, v59
	v_mov_b32_e32 v80, v61
	s_cbranch_scc0 .LBB0_447
.LBB0_443:
	v_mov_b32_e32 v59, v129
	v_lshl_add_u64 v[62:63], v[62:63], 0, v[58:59]
	v_mov_b32_e32 v61, v129
	v_lshl_add_u64 v[82:83], v[64:65], 0, v[128:129]
	v_lshl_add_u64 v[62:63], v[62:63], 0, v[60:61]
	global_load_dwordx4 v[64:67], v[82:83], off offset:16
	s_nop 0
	global_load_dwordx4 v[82:85], v[82:83], off
	s_nop 0
	global_load_dwordx4 v[86:89], v[62:63], off offset:64
	global_load_dwordx4 v[90:93], v[62:63], off
	s_barrier
	s_mov_b32 s2, s24
	s_add_i32 s24, s24, 1
	s_cmp_lt_u32 s2, 7
	s_cselect_b32 s2, s24, s2
	s_lshl_b32 s3, s2, 5
	s_add_i32 s25, s3, 0xffffff00
	s_cmp_lt_u32 s2, 8
	s_cselect_b32 s3, s3, s25
	s_cmp_gt_u32 s2, 7
	s_waitcnt vmcnt(0)
	v_and_b32_sdwa v62, v93, v170 dst_sel:DWORD dst_unused:UNUSED_PAD src0_sel:WORD_1 src1_sel:DWORD
	v_and_b32_sdwa v63, v91, v170 dst_sel:DWORD dst_unused:UNUSED_PAD src0_sel:WORD_1 src1_sel:DWORD
	v_and_b32_sdwa v59, v92, v170 dst_sel:DWORD dst_unused:UNUSED_PAD src0_sel:WORD_1 src1_sel:DWORD
	v_and_b32_sdwa v61, v90, v170 dst_sel:DWORD dst_unused:UNUSED_PAD src0_sel:WORD_1 src1_sel:DWORD
	v_add3_u32 v62, v93, v62, s56
	v_add3_u32 v63, v91, v63, s56
	v_add3_u32 v61, v90, v61, s56
	v_add3_u32 v59, v92, v59, s56
	v_and_b32_e32 v62, 0xffff0000, v62
	v_and_b32_e32 v90, 0xffff0000, v63
	v_or_b32_sdwa v63, v62, v59 dst_sel:DWORD dst_unused:UNUSED_PAD src0_sel:DWORD src1_sel:WORD_1
	v_or_b32_sdwa v62, v90, v61 dst_sel:DWORD dst_unused:UNUSED_PAD src0_sel:DWORD src1_sel:WORD_1
	ds_write_b64 v74, v[62:63]
	v_and_b32_sdwa v62, v89, v170 dst_sel:DWORD dst_unused:UNUSED_PAD src0_sel:WORD_1 src1_sel:DWORD
	v_and_b32_sdwa v59, v88, v170 dst_sel:DWORD dst_unused:UNUSED_PAD src0_sel:WORD_1 src1_sel:DWORD
	v_and_b32_sdwa v63, v87, v170 dst_sel:DWORD dst_unused:UNUSED_PAD src0_sel:WORD_1 src1_sel:DWORD
	v_add3_u32 v62, v89, v62, s56
	v_and_b32_sdwa v61, v86, v170 dst_sel:DWORD dst_unused:UNUSED_PAD src0_sel:WORD_1 src1_sel:DWORD
	v_add3_u32 v59, v88, v59, s56
	v_add3_u32 v63, v87, v63, s56
	v_and_b32_e32 v62, 0xffff0000, v62
	v_add3_u32 v61, v86, v61, s56
	v_and_b32_e32 v86, 0xffff0000, v63
	v_or_b32_sdwa v63, v62, v59 dst_sel:DWORD dst_unused:UNUSED_PAD src0_sel:DWORD src1_sel:WORD_1
	v_bfe_u32 v59, v82, 16, 1
	v_or_b32_sdwa v62, v86, v61 dst_sel:DWORD dst_unused:UNUSED_PAD src0_sel:DWORD src1_sel:WORD_1
	v_add3_u32 v59, v82, v59, s56
	ds_write_b64 v75, v[62:63]
	ds_write_b16_d16_hi v76, v59 offset:4096
	v_bfe_u32 v59, v64, 16, 1
	v_add3_u32 v59, v64, v59, s56
	ds_write_b16_d16_hi v76, v59 offset:4352
	v_bfe_u32 v59, v83, 16, 1
	v_add3_u32 v59, v83, v59, s56
	ds_write_b16_d16_hi v76, v59 offset:4160
	v_bfe_u32 v59, v65, 16, 1
	v_add3_u32 v59, v65, v59, s56
	ds_write_b16_d16_hi v76, v59 offset:4416
	v_bfe_u32 v59, v84, 16, 1
	v_add3_u32 v59, v84, v59, s56
	ds_write_b16_d16_hi v76, v59 offset:4224
	v_bfe_u32 v59, v66, 16, 1
	v_add3_u32 v59, v66, v59, s56
	ds_write_b16_d16_hi v76, v59 offset:4480
	v_bfe_u32 v59, v85, 16, 1
	v_add3_u32 v59, v85, v59, s56
	ds_write_b16_d16_hi v76, v59 offset:4288
	v_bfe_u32 v59, v67, 16, 1
	v_add3_u32 v59, v67, v59, s56
	v_add_u32_e32 v66, s3, v73
	s_mov_b64 s[2:3], -1
	ds_write_b16_d16_hi v76, v59 offset:4544
	s_waitcnt lgkmcnt(0)
	s_barrier
	s_cbranch_scc0 .LBB0_445
	v_ashrrev_i32_e32 v67, 31, v66
	v_lshl_add_u64 v[62:63], v[66:67], 0, v[54:55]
	v_lshlrev_b64 v[64:65], 9, v[62:63]
	v_readlane_b32 s68, v253, 56
	v_lshl_or_b32 v64, v52, 2, v64
	v_readlane_b32 s74, v253, 62
	v_readlane_b32 s75, v253, 63
	v_readlane_b32 s76, v254, 0
	v_readlane_b32 s77, v254, 1
	v_readlane_b32 s69, v253, 57
	v_readlane_b32 s70, v253, 58
	v_readlane_b32 s71, v253, 59
	v_readlane_b32 s72, v253, 60
	v_readlane_b32 s73, v253, 61
	v_readlane_b32 s78, v254, 2
	v_readlane_b32 s79, v254, 3
	v_readlane_b32 s80, v254, 4
	v_readlane_b32 s81, v254, 5
	v_readlane_b32 s82, v254, 6
	v_readlane_b32 s83, v254, 7
	v_lshl_add_u64 v[62:63], s[74:75], 0, v[64:65]
	v_lshl_add_u64 v[64:65], s[76:77], 0, v[64:65]
	s_mov_b64 s[2:3], 0

.LBB0_507:
	s_andn2_saveexec_b64 s[2:3], s[16:17]
	s_cbranch_execz .LBB0_525
	v_lshlrev_b32_e32 v0, 5, v32
	v_and_b32_e32 v107, 0x3e0, v0
	v_add_u32_e32 v0, 0xbf, v107
	s_movk_i32 s0, 0x80
	v_and_b32_e32 v0, 0x7e0, v0
	v_sub_u32_e64 v120, v107, s0 clamp
	v_min_u32_e32 v0, 0x400, v0
	v_mov_b32_e32 v67, v166
	v_sub_u32_e32 v0, v0, v120
	v_ashrrev_i32_e32 v121, 5, v0
	v_bfe_u32 v65, v67, 4, 2
	v_cmp_eq_u32_e32 vcc, 0, v65
	v_cmp_gt_i32_e64 s[0:1], -7, v121
	v_lshlrev_b32_e32 v119, 2, v65
	s_and_saveexec_b64 s[24:25], s[0:1]
	s_xor_b64 s[0:1], exec, s[24:25]
	v_mbcnt_lo_u32_b32 v0, -1, 0
	v_mbcnt_hi_u32_b32 v33, -1, v0
	v_and_b32_e32 v0, 64, v33
	v_xor_b32_e32 v130, 16, v33
	v_add_u32_e32 v34, 64, v0
	v_xor_b32_e32 v127, 32, v33
	v_lshlrev_b32_e32 v128, 2, v65
	s_or_saveexec_b64 s[24:25], s[0:1]
	v_add_u32_e32 v0, 0xffffff80, v32
	v_lshrrev_b32_e32 v68, 6, v0
	v_bfe_u32 v69, v32, 5, 1
	v_ashrrev_i32_e32 v0, 6, v67
	v_lshl_add_u32 v72, v69, 2, v0
	v_mov_b32_e32 v0, 0x2000
	v_lshlrev_b32_e32 v104, 6, v72
	v_cndmask_b32_e64 v126, 0, 1.0, vcc
	v_mov_b32_e32 v31, 0
	v_and_b32_e32 v109, 15, v67
	v_lshl_add_u32 v118, v68, 10, v0
	v_ashrrev_i32_e32 v105, 31, v104
	v_mov_b32_e32 v30, v31
	v_mov_b32_e32 v29, v31
	v_mov_b32_e32 v28, v31
	v_mov_b32_e32 v27, v31
	v_mov_b32_e32 v26, v31
	v_mov_b32_e32 v25, v31
	v_mov_b32_e32 v24, v31
	v_mov_b32_e32 v23, v31
	v_mov_b32_e32 v22, v31
	v_mov_b32_e32 v21, v31
	v_mov_b32_e32 v20, v31
	v_mov_b32_e32 v19, v31
	v_mov_b32_e32 v18, v31
	v_mov_b32_e32 v17, v31
	v_mov_b32_e32 v16, v31
	v_mov_b32_e32 v15, v31
	v_mov_b32_e32 v14, v31
	v_mov_b32_e32 v13, v31
	v_mov_b32_e32 v12, v31
	v_mov_b32_e32 v11, v31
	v_mov_b32_e32 v10, v31
	v_mov_b32_e32 v9, v31
	v_mov_b32_e32 v8, v31
	v_mov_b32_e32 v7, v31
	v_mov_b32_e32 v6, v31
	v_mov_b32_e32 v5, v31
	v_mov_b32_e32 v4, v31
	v_mov_b32_e32 v3, v31
	v_mov_b32_e32 v2, v31
	v_mov_b32_e32 v1, v31
	v_mov_b32_e32 v0, v31
	v_mov_b32_e32 v88, v126
	s_xor_b64 exec, exec, s[24:25]
	s_cbranch_execz .LBB0_524
	v_or_b32_e32 v122, v109, v107
	v_or_b32_e32 v123, 16, v122
	v_lshlrev_b32_e32 v0, 2, v67
	v_lshrrev_b32_e32 v71, 4, v67
	v_and_b32_e32 v106, 12, v0
	v_or_b32_e32 v0, v123, v118
	v_lshl_add_u64 v[34:35], v[104:105], 2, s[30:31]
	v_lshlrev_b32_e32 v128, 13, v0
	v_lshlrev_b32_e32 v11, 3, v71
	v_lshl_add_u64 v[8:9], v[34:35], 0, v[128:129]
	v_lshlrev_b32_e32 v128, 5, v65
	v_lshlrev_b32_e32 v10, 4, v123
	v_and_b32_e32 v44, 8, v11
	s_movk_i32 s0, 0x3f0
	v_and_or_b32 v10, v10, s0, v44
	v_xor_b32_e32 v40, 64, v128
	v_mov_b32_e32 v41, v129
	v_lshl_add_u64 v[20:21], v[8:9], 0, v[128:129]
	v_lshlrev_b32_e32 v81, 3, v10
	v_and_b32_e32 v10, 32, v67
	v_lshl_add_u64 v[28:29], v[8:9], 0, v[40:41]
	global_load_dwordx4 v[0:3], v[20:21], off offset:144
	global_load_dwordx4 v[4:7], v[20:21], off offset:128
	v_cmp_eq_u32_e32 vcc, 0, v10
	global_load_dwordx4 v[8:11], v[28:29], off offset:144
	global_load_dwordx4 v[12:15], v[28:29], off offset:128
	global_load_dwordx4 v[16:19], v[20:21], off offset:16
	global_load_dwordx4 v[24:27], v[20:21], off
	v_lshlrev_b32_e32 v20, 3, v32
	s_movk_i32 s0, 0xf0
	v_or_b32_e32 v32, v122, v118
	v_and_or_b32 v20, v20, s0, v44
	v_lshlrev_b32_e32 v32, 13, v32
	v_mov_b32_e32 v33, v129
	v_lshlrev_b32_e32 v45, 4, v122
	s_movk_i32 s0, 0x2f0
	v_lshl_add_u64 v[42:43], v[34:35], 0, v[32:33]
	v_and_or_b32 v44, v45, s0, v44
	v_readlane_b32 s0, v250, 31
	v_lshl_add_u64 v[62:63], v[42:43], 0, v[128:129]
	v_lshlrev_b32_e32 v61, 3, v44
	v_lshl_add_u64 v[82:83], v[42:43], 0, v[40:41]
	v_readlane_b32 s1, v250, 32
	v_lshlrev_b32_e32 v60, 3, v20
	global_load_dwordx4 v[20:23], v[28:29], off offset:16
	s_nop 0
	global_load_dwordx4 v[28:31], v[28:29], off
	s_nop 0
	global_load_dwordx4 v[32:35], v[62:63], off offset:144
	global_load_dwordx4 v[36:39], v[62:63], off offset:128
	global_load_dwordx4 v[40:43], v[82:83], off offset:144
	global_load_dwordx4 v[44:47], v[82:83], off offset:128
	global_load_dwordx4 v[48:51], v61, s[0:1] offset:48
	global_load_dwordx4 v[52:55], v61, s[0:1] offset:32
	global_load_dwordx4 v[56:59], v61, s[0:1] offset:16
	global_load_dwordx4 v[74:77], v61, s[0:1]
	s_mov_b32 s16, 0x3e000000
	v_readlane_b32 s68, v254, 8
	v_readlane_b32 s69, v254, 9
	v_ashrrev_i32_e32 v125, 3, v67
	v_and_b32_e32 v70, 7, v67
	v_lshlrev_b32_e32 v128, 8, v69
	v_lshlrev_b32_e32 v64, 3, v70
	v_and_b32_e32 v66, 32, v64
	v_xor_b32_e32 v130, 16, v176
	v_xor_b32_e32 v127, 32, v176
	v_add_u32_e32 v124, 8, v121
	v_lshlrev_b32_e32 v108, 6, v69
	s_mov_b32 s26, 0
	v_mov_b32_e32 v111, v129
	v_add_u32_e32 v134, -2, v122
	v_add_u32_e32 v135, -3, v122
	v_add_u32_e32 v136, -16, v122
	v_subrev_u32_e32 v137, 17, v122
	v_subrev_u32_e32 v138, 18, v122
	v_subrev_u32_e32 v139, 19, v122
	v_add_u32_e32 v140, 14, v122
	v_add_u32_e32 v141, 13, v122
	v_lshl_add_u64 v[112:113], s[30:31], 0, v[128:129]
	s_mov_b64 s[40:41], 0
	v_lshlrev_b32_e32 v114, 2, v106
	v_lshlrev_b32_e32 v116, 2, v64
	v_mov_b32_e32 v149, v120
	v_mov_b32_e32 v150, v126
	v_readlane_b32 s70, v254, 10
	v_readlane_b32 s71, v254, 11
	v_readlane_b32 s72, v254, 12
	v_readlane_b32 s73, v254, 13
	v_readlane_b32 s74, v254, 14
	v_readlane_b32 s75, v254, 15
	v_readlane_b32 s76, v254, 16
	v_readlane_b32 s77, v254, 17
	v_readlane_b32 s78, v254, 18
	v_readlane_b32 s79, v254, 19
	v_readlane_b32 s80, v254, 20
	v_readlane_b32 s81, v254, 21
	v_readlane_b32 s82, v254, 22
	v_readlane_b32 s83, v254, 23
	s_waitcnt vmcnt(13)
	v_cndmask_b32_e64 v9, v9, -v9, vcc
	s_waitcnt vmcnt(12)
	v_cndmask_b32_e64 v13, v13, -v13, vcc
	v_cndmask_b32_e64 v12, v12, -v12, vcc
	v_cndmask_b32_e64 v15, v15, -v15, vcc
	v_cndmask_b32_e64 v14, v14, -v14, vcc
	v_cndmask_b32_e64 v8, v8, -v8, vcc
	v_cndmask_b32_e64 v11, v11, -v11, vcc
	v_cndmask_b32_e64 v10, v10, -v10, vcc
	s_waitcnt vmcnt(9)
	v_cndmask_b32_e64 v21, v21, -v21, vcc
	s_waitcnt vmcnt(8)
	v_cndmask_b32_e64 v29, v29, -v29, vcc
	s_waitcnt vmcnt(5)
	v_cndmask_b32_e64 v41, v41, -v41, vcc
	s_waitcnt vmcnt(4)
	v_cndmask_b32_e64 v45, v45, -v45, vcc
	s_waitcnt vmcnt(0)
	v_mov_b32_e32 v79, v76
	v_cndmask_b32_e64 v44, v44, -v44, vcc
	v_mov_b32_e32 v76, v75
	v_mov_b32_e32 v78, v74
	v_pk_mul_f32 v[44:45], v[76:77], v[44:45]
	v_cndmask_b32_e64 v47, v47, -v47, vcc
	v_pk_fma_f32 v[36:37], v[36:37], v[78:79], v[44:45]
	v_mov_b32_e32 v45, v58
	v_cndmask_b32_e64 v46, v46, -v46, vcc
	v_mov_b32_e32 v58, v57
	v_mov_b32_e32 v44, v56
	v_pk_mul_f32 v[46:47], v[46:47], v[58:59]
	v_cndmask_b32_e64 v40, v40, -v40, vcc
	v_pk_fma_f32 v[38:39], v[38:39], v[44:45], v[46:47]
	v_mov_b32_e32 v45, v54
	v_mov_b32_e32 v54, v53
	v_mov_b32_e32 v44, v52
	v_pk_mul_f32 v[40:41], v[54:55], v[40:41]
	v_cndmask_b32_e64 v43, v43, -v43, vcc
	v_pk_fma_f32 v[32:33], v[32:33], v[44:45], v[40:41]
	v_mov_b32_e32 v41, v50
	v_cndmask_b32_e64 v42, v42, -v42, vcc
	v_mov_b32_e32 v50, v49
	v_mov_b32_e32 v40, v48
	v_pk_mul_f32 v[42:43], v[42:43], v[50:51]
	v_pk_mul_f32 v[36:37], v[36:37], s[16:17] op_sel_hi:[1,0]
	v_pk_fma_f32 v[34:35], v[34:35], v[40:41], v[42:43]
	v_pk_mul_f32 v[38:39], v[38:39], s[16:17] op_sel_hi:[1,0]
	v_pk_mul_f32 v[32:33], v[32:33], s[16:17] op_sel_hi:[1,0]
	v_pk_mul_f32 v[34:35], v[34:35], s[16:17] op_sel_hi:[1,0]
	v_bfe_u32 v42, v33, 16, 1
	v_bfe_u32 v40, v35, 16, 1
	v_bfe_u32 v41, v34, 16, 1
	v_bfe_u32 v43, v32, 16, 1
	v_bfe_u32 v44, v39, 16, 1
	v_bfe_u32 v45, v38, 16, 1
	v_bfe_u32 v46, v37, 16, 1
	v_bfe_u32 v47, v36, 16, 1
	v_add3_u32 v73, v36, v47, s56
	v_add3_u32 v74, v37, v46, s56
	v_add3_u32 v75, v38, v45, s56
	v_add3_u32 v76, v39, v44, s56
	v_add3_u32 v77, v32, v43, s56
	v_add3_u32 v78, v33, v42, s56
	v_add3_u32 v79, v34, v41, s56
	v_add3_u32 v80, v35, v40, s56
	global_load_dwordx4 v[32:35], v[62:63], off offset:16
	global_load_dwordx4 v[48:51], v[62:63], off
	global_load_dwordx4 v[36:39], v[82:83], off offset:16
	global_load_dwordx4 v[52:55], v[82:83], off
	global_load_dwordx4 v[40:43], v60, s[0:1] offset:48
	global_load_dwordx4 v[44:47], v60, s[0:1] offset:32
	global_load_dwordx4 v[56:59], v60, s[0:1] offset:16
	s_nop 0
	global_load_dwordx4 v[60:63], v60, s[0:1]
	v_cndmask_b32_e64 v28, v28, -v28, vcc
	v_cndmask_b32_e64 v31, v31, -v31, vcc
	v_cndmask_b32_e64 v30, v30, -v30, vcc
	v_cndmask_b32_e64 v20, v20, -v20, vcc
	v_cndmask_b32_e64 v23, v23, -v23, vcc
	v_cndmask_b32_e64 v22, v22, -v22, vcc
	s_waitcnt vmcnt(0)
	v_mov_b32_e32 v83, v62
	v_mov_b32_e32 v62, v61
	v_mov_b32_e32 v82, v60
	v_pk_mul_f32 v[28:29], v[62:63], v[28:29]
	s_nop 0
	v_pk_fma_f32 v[24:25], v[24:25], v[82:83], v[28:29]
	v_cndmask_b32_e64 v29, v53, -v53, vcc
	v_cndmask_b32_e64 v28, v52, -v52, vcc
	v_pk_mul_f32 v[28:29], v[62:63], v[28:29]
	v_pk_mul_f32 v[24:25], v[24:25], s[16:17] op_sel_hi:[1,0]
	v_pk_fma_f32 v[28:29], v[82:83], v[48:49], v[28:29]
	v_mov_b32_e32 v49, v58
	v_mov_b32_e32 v58, v57
	v_mov_b32_e32 v48, v56
	v_pk_mul_f32 v[30:31], v[30:31], v[58:59]
	v_pk_mul_f32 v[28:29], v[28:29], s[16:17] op_sel_hi:[1,0]
	v_pk_fma_f32 v[26:27], v[26:27], v[48:49], v[30:31]
	v_cndmask_b32_e64 v31, v55, -v55, vcc
	v_cndmask_b32_e64 v30, v54, -v54, vcc
	v_pk_mul_f32 v[30:31], v[58:59], v[30:31]
	v_pk_mul_f32 v[26:27], v[26:27], s[16:17] op_sel_hi:[1,0]
	v_pk_fma_f32 v[30:31], v[48:49], v[50:51], v[30:31]
	v_mov_b32_e32 v49, v46
	v_mov_b32_e32 v46, v45
	v_mov_b32_e32 v48, v44
	v_pk_mul_f32 v[20:21], v[46:47], v[20:21]
	v_pk_mul_f32 v[30:31], v[30:31], s[16:17] op_sel_hi:[1,0]
	v_pk_fma_f32 v[16:17], v[16:17], v[48:49], v[20:21]
	v_cndmask_b32_e64 v21, v37, -v37, vcc
	v_cndmask_b32_e64 v20, v36, -v36, vcc
	v_pk_mul_f32 v[16:17], v[16:17], s[16:17] op_sel_hi:[1,0]
	v_pk_mul_f32 v[20:21], v[46:47], v[20:21]
	v_bfe_u32 v36, v17, 16, 1
	v_pk_fma_f32 v[20:21], v[48:49], v[32:33], v[20:21]
	v_mov_b32_e32 v33, v42
	v_mov_b32_e32 v42, v41
	v_bfe_u32 v37, v16, 16, 1
	v_mov_b32_e32 v32, v40
	v_pk_mul_f32 v[22:23], v[22:23], v[42:43]
	v_add3_u32 v46, v16, v37, s56
	v_add3_u32 v47, v17, v36, s56
	v_cndmask_b32_e64 v17, v39, -v39, vcc
	v_cndmask_b32_e64 v16, v38, -v38, vcc
	v_pk_fma_f32 v[18:19], v[18:19], v[32:33], v[22:23]
	v_pk_mul_f32 v[16:17], v[42:43], v[16:17]
	v_pk_mul_f32 v[18:19], v[18:19], s[16:17] op_sel_hi:[1,0]
	v_pk_fma_f32 v[16:17], v[32:33], v[34:35], v[16:17]
	v_pk_mul_f32 v[20:21], v[20:21], s[16:17] op_sel_hi:[1,0]
	v_bfe_u32 v22, v19, 16, 1
	v_bfe_u32 v23, v18, 16, 1
	v_bfe_u32 v45, v27, 16, 1
	v_bfe_u32 v41, v26, 16, 1
	v_bfe_u32 v44, v25, 16, 1
	v_bfe_u32 v40, v24, 16, 1
	v_pk_mul_f32 v[16:17], v[16:17], s[16:17] op_sel_hi:[1,0]
	v_add3_u32 v40, v24, v40, s56
	v_add3_u32 v44, v25, v44, s56
	v_add3_u32 v41, v26, v41, s56
	v_add3_u32 v45, v27, v45, s56
	v_add3_u32 v82, v18, v23, s56
	v_add3_u32 v83, v19, v22, s56
	v_bfe_u32 v18, v17, 16, 1
	v_bfe_u32 v19, v16, 16, 1
	v_bfe_u32 v22, v21, 16, 1
	v_bfe_u32 v23, v20, 16, 1
	v_bfe_u32 v24, v31, 16, 1
	v_bfe_u32 v25, v30, 16, 1
	v_bfe_u32 v26, v29, 16, 1
	v_bfe_u32 v27, v28, 16, 1
	v_add3_u32 v32, v28, v27, s56
	v_add3_u32 v36, v29, v26, s56
	v_add3_u32 v33, v30, v25, s56
	v_add3_u32 v37, v31, v24, s56
	v_add3_u32 v34, v20, v23, s56
	v_add3_u32 v38, v21, v22, s56
	v_add3_u32 v35, v16, v19, s56
	v_add3_u32 v39, v17, v18, s56
	global_load_dwordx4 v[16:19], v81, s[0:1] offset:48
	global_load_dwordx4 v[20:23], v81, s[0:1] offset:32
	global_load_dwordx4 v[24:27], v81, s[0:1] offset:16
	global_load_dwordx4 v[28:31], v81, s[0:1]
	v_readlane_b32 s0, v254, 56
	v_cmp_gt_u32_e32 vcc, 4, v70
	s_waitcnt vmcnt(0)
	v_mov_b32_e32 v43, v30
	v_mov_b32_e32 v30, v29
	v_mov_b32_e32 v42, v28
	v_pk_mul_f32 v[12:13], v[12:13], v[30:31]
	s_nop 0
	v_pk_fma_f32 v[4:5], v[4:5], v[42:43], v[12:13]
	v_mov_b32_e32 v13, v26
	v_mov_b32_e32 v26, v25
	v_mov_b32_e32 v12, v24
	v_pk_mul_f32 v[14:15], v[14:15], v[26:27]
	v_pk_mul_f32 v[4:5], v[4:5], s[16:17] op_sel_hi:[1,0]
	v_pk_fma_f32 v[6:7], v[6:7], v[12:13], v[14:15]
	v_mov_b32_e32 v13, v22
	v_mov_b32_e32 v22, v21
	v_mov_b32_e32 v12, v20
	v_pk_mul_f32 v[8:9], v[8:9], v[22:23]
	v_pk_mul_f32 v[6:7], v[6:7], s[16:17] op_sel_hi:[1,0]
	v_pk_fma_f32 v[0:1], v[0:1], v[12:13], v[8:9]
	v_mov_b32_e32 v9, v18
	v_mov_b32_e32 v18, v17
	v_pk_mul_f32 v[0:1], v[0:1], s[16:17] op_sel_hi:[1,0]
	v_mov_b32_e32 v8, v16
	v_pk_mul_f32 v[10:11], v[10:11], v[18:19]
	v_bfe_u32 v13, v6, 16, 1
	v_pk_fma_f32 v[2:3], v[2:3], v[8:9], v[10:11]
	v_bfe_u32 v11, v0, 16, 1
	v_bfe_u32 v10, v1, 16, 1
	v_add3_u32 v11, v0, v11, s56
	v_add_u32_e32 v0, s0, v72
	v_add3_u32 v10, v1, v10, s56
	v_ashrrev_i32_e32 v1, 31, v0
	v_lshl_add_u64 v[0:1], v[0:1], 2, s[68:69]
	global_load_dword v152, v[0:1], off
	v_or_b32_e32 v0, v118, v120
	v_add_u32_e32 v0, v0, v125
	v_ashrrev_i32_e32 v1, 31, v0
	v_pk_mul_f32 v[2:3], v[2:3], s[16:17] op_sel_hi:[1,0]
	v_lshlrev_b64 v[0:1], 13, v[0:1]
	v_bfe_u32 v8, v3, 16, 1
	v_bfe_u32 v9, v2, 16, 1
	v_lshl_add_u64 v[0:1], s[30:31], 0, v[0:1]
	v_add3_u32 v9, v2, v9, s56
	v_add3_u32 v8, v3, v8, s56
	v_lshl_add_u64 v[0:1], v[0:1], 0, v[128:129]
	v_lshlrev_b32_e32 v2, 5, v70
	v_mov_b32_e32 v3, v129
	v_lshl_add_u64 v[2:3], v[0:1], 0, v[2:3]
	global_load_dwordx4 v[48:51], v[2:3], off offset:2576
	global_load_dwordx4 v[52:55], v[2:3], off offset:2560
	v_lshlrev_b32_e32 v2, 2, v66
	v_mov_b32_e32 v3, v129
	v_lshl_add_u64 v[0:1], v[0:1], 0, v[2:3]
	v_lshlrev_b32_e32 v2, 2, v106
	v_lshl_add_u64 v[0:1], v[0:1], 0, v[2:3]
	global_load_dwordx4 v[56:59], v[0:1], off offset:2112
	global_load_dwordx4 v[60:63], v[0:1], off offset:2048
	v_or_b32_e32 v1, v66, v106
	v_bfe_u32 v0, v67, 4, 3
	v_lshrrev_b32_e32 v1, 3, v1
	v_lshl_add_u32 v2, v125, 7, 0
	v_bitop3_b32 v0, v1, v0, 2 bitop3:0x36
	v_bitop3_b32 v3, v1, v71, 7 bitop3:0x78
	v_lshl_add_u32 v1, v0, 4, v2
	v_readlane_b32 s0, v254, 63
	v_lshrrev_b32_e32 v0, 1, v67
	v_add3_u32 v6, v6, v13, s56
	v_lshl_or_b32 v110, v68, 9, s0
	v_bfe_u32 v13, v67, 1, 3
	v_cmp_lt_i32_e64 s[0:1], v130, v177
	v_bitop3_b32 v0, v65, v0, 7 bitop3:0x78
	v_bfe_u32 v12, v7, 16, 1
	v_cndmask_b32_e64 v16, v176, v130, s[0:1]
	v_cmp_lt_i32_e64 s[0:1], v127, v177
	v_lshlrev_b32_e32 v17, 4, v0
	v_bitop3_b32 v0, v65, v13, 4 bitop3:0x36
	v_bfe_u32 v14, v5, 16, 1
	v_bfe_u32 v15, v4, 16, 1
	v_add3_u32 v7, v7, v12, s56
	v_lshlrev_b32_e32 v12, 3, v67
	v_lshlrev_b32_e32 v132, 2, v16
	v_cndmask_b32_e64 v16, v176, v127, s[0:1]
	s_movk_i32 s0, 0x280
	v_lshlrev_b32_e32 v13, 4, v0
	v_lshlrev_b32_e32 v0, 5, v121
	v_add3_u32 v4, v4, v15, s56
	v_add3_u32 v5, v5, v14, s56
	v_lshl_add_u32 v3, v3, 4, v2
	v_and_b32_e32 v12, 8, v12
	v_lshlrev_b32_e32 v2, 1, v125
	v_lshl_add_u32 v14, v109, 7, 0
	v_lshl_add_u32 v15, v65, 3, 0
	v_lshlrev_b32_e32 v133, 2, v16
	v_mad_u32_u24 v16, v70, s0, 0
	v_mul_u32_u24_e32 v18, 0x50, v109
	s_mov_b32 s0, 0x7060302
	v_sub_u32_e32 v142, 0, v0
	v_mov_b32_e32 v0, 0
	v_perm_b32 v35, v39, v35, s0
	v_perm_b32 v34, v38, v34, s0
	v_perm_b32 v33, v37, v33, s0
	v_perm_b32 v32, v36, v32, s0
	v_perm_b32 v39, v80, v79, s0
	v_perm_b32 v38, v78, v77, s0
	v_perm_b32 v37, v76, v75, s0
	v_perm_b32 v36, v74, v73, s0
	v_perm_b32 v43, v83, v82, s0
	v_perm_b32 v42, v47, v46, s0
	v_perm_b32 v41, v45, v41, s0
	v_perm_b32 v40, v44, v40, s0
	v_perm_b32 v47, v8, v9, s0
	v_perm_b32 v46, v10, v11, s0
	v_perm_b32 v45, v7, v6, s0
	v_perm_b32 v44, v5, v4, s0
	v_add_u32_e32 v143, v3, v12
	v_add_u32_e32 v144, v1, v12
	v_add_u32_e32 v145, v16, v2
	v_and_b32_e32 v145, 7, v166
	v_lshlrev_b32_e32 v145, 9, v145
	v_lshrrev_b32_e32 v146, 5, v166
	v_xor_b32_e32 v146, v146, v166
	v_and_b32_e32 v146, 7, v146
	v_lshl_or_b32 v145, v146, 3, v145
	v_bfe_u32 v146, v166, 3, 2
	v_lshl_or_b32 v145, v146, 1, v145
	v_lshlrev_b32_e32 v128, 2, v66
	v_add_u32_e32 v146, v14, v17
	v_add_u32_e32 v147, v14, v13
	v_add_u32_e32 v148, v15, v18
	v_bfe_u32 v148, v166, 4, 2
	v_bfe_u32 v18, v166, 3, 1
	v_xor_b32_e32 v148, v148, v18
	v_lshlrev_b32_e32 v148, 3, v148
	v_and_b32_e32 v18, 15, v166
	v_lshl_or_b32 v148, v18, 6, v148
	s_waitcnt vmcnt(4)
	v_mov_b32_e32 v151, v152
	v_mov_b32_e32 v1, v0
	v_mov_b32_e32 v2, v0
	v_mov_b32_e32 v3, v0
	v_mov_b32_e32 v4, v0
	v_mov_b32_e32 v5, v0
	v_mov_b32_e32 v6, v0
	v_mov_b32_e32 v7, v0
	v_mov_b32_e32 v8, v0
	v_mov_b32_e32 v9, v0
	v_mov_b32_e32 v10, v0
	v_mov_b32_e32 v11, v0
	v_mov_b32_e32 v12, v0
	v_mov_b32_e32 v13, v0
	v_mov_b32_e32 v14, v0
	v_mov_b32_e32 v15, v0
	v_mov_b32_e32 v16, v0
	v_mov_b32_e32 v17, v0
	v_mov_b32_e32 v18, v0
	v_mov_b32_e32 v19, v0
	v_mov_b32_e32 v20, v0
	v_mov_b32_e32 v21, v0
	v_mov_b32_e32 v22, v0
	v_mov_b32_e32 v23, v0
	v_mov_b32_e32 v24, v0
	v_mov_b32_e32 v25, v0
	v_mov_b32_e32 v26, v0
	v_mov_b32_e32 v27, v0
	v_mov_b32_e32 v28, v0
	v_mov_b32_e32 v29, v0
	v_mov_b32_e32 v30, v0
	v_mov_b32_e32 v31, v0
	s_branch .LBB0_513

.LBB0_515:
	s_or_b64 exec, exec, s[28:29]
	s_waitcnt vmcnt(0)
	v_and_b32_sdwa v64, v62, v170 dst_sel:DWORD dst_unused:UNUSED_PAD src0_sel:WORD_1 src1_sel:DWORD
	v_and_b32_sdwa v65, v60, v170 dst_sel:DWORD dst_unused:UNUSED_PAD src0_sel:WORD_1 src1_sel:DWORD
	v_add3_u32 v60, v60, v65, s56
	v_add3_u32 v62, v62, v64, s56
	v_and_b32_sdwa v64, v63, v170 dst_sel:DWORD dst_unused:UNUSED_PAD src0_sel:WORD_1 src1_sel:DWORD
	v_and_b32_sdwa v65, v61, v170 dst_sel:DWORD dst_unused:UNUSED_PAD src0_sel:WORD_1 src1_sel:DWORD
	v_add3_u32 v63, v63, v64, s56
	v_add3_u32 v61, v61, v65, s56
	v_and_b32_e32 v63, 0xffff0000, v63
	v_and_b32_e32 v64, 0xffff0000, v61
	v_or_b32_sdwa v61, v63, v62 dst_sel:DWORD dst_unused:UNUSED_PAD src0_sel:DWORD src1_sel:WORD_1
	v_or_b32_sdwa v60, v64, v60 dst_sel:DWORD dst_unused:UNUSED_PAD src0_sel:DWORD src1_sel:WORD_1
	ds_write_b64 v143, v[60:61]
	v_and_b32_sdwa v60, v58, v170 dst_sel:DWORD dst_unused:UNUSED_PAD src0_sel:WORD_1 src1_sel:DWORD
	v_and_b32_sdwa v61, v56, v170 dst_sel:DWORD dst_unused:UNUSED_PAD src0_sel:WORD_1 src1_sel:DWORD
	v_add3_u32 v56, v56, v61, s56
	v_add3_u32 v58, v58, v60, s56
	v_and_b32_sdwa v60, v59, v170 dst_sel:DWORD dst_unused:UNUSED_PAD src0_sel:WORD_1 src1_sel:DWORD
	v_and_b32_sdwa v61, v57, v170 dst_sel:DWORD dst_unused:UNUSED_PAD src0_sel:WORD_1 src1_sel:DWORD
	v_add3_u32 v59, v59, v60, s56
	v_add3_u32 v57, v57, v61, s56
	v_and_b32_e32 v59, 0xffff0000, v59
	v_and_b32_e32 v60, 0xffff0000, v57
	v_or_b32_sdwa v57, v59, v58 dst_sel:DWORD dst_unused:UNUSED_PAD src0_sel:DWORD src1_sel:WORD_1
	v_or_b32_sdwa v56, v60, v56 dst_sel:DWORD dst_unused:UNUSED_PAD src0_sel:DWORD src1_sel:WORD_1
	ds_write_b64 v144, v[56:57]
	v_bfe_u32 v56, v52, 16, 1
	v_add3_u32 v52, v52, v56, s56
	ds_write_b16_d16_hi v145, v52 offset:4096
	v_bfe_u32 v52, v48, 16, 1
	v_add3_u32 v48, v48, v52, s56
	ds_write_b16_d16_hi v145, v48 offset:4352
	v_bfe_u32 v48, v53, 16, 1
	v_add3_u32 v48, v53, v48, s56
	ds_write_b16_d16_hi v145, v48 offset:4160
	v_bfe_u32 v48, v49, 16, 1
	v_add3_u32 v48, v49, v48, s56
	ds_write_b16_d16_hi v145, v48 offset:4416
	v_bfe_u32 v48, v54, 16, 1
	v_add3_u32 v48, v54, v48, s56
	ds_write_b16_d16_hi v145, v48 offset:4224
	v_bfe_u32 v48, v50, 16, 1
	v_add3_u32 v48, v50, v48, s56
	ds_write_b16_d16_hi v145, v48 offset:4480
	v_bfe_u32 v48, v55, 16, 1
	v_add3_u32 v48, v55, v48, s56
	ds_write_b16_d16_hi v145, v48 offset:4288
	v_bfe_u32 v48, v51, 16, 1
	v_add3_u32 v48, v51, v48, s56
	s_add_i32 s27, s26, 1
	ds_write_b16_d16_hi v145, v48 offset:4544
	v_mov_b32_e32 v48, s26
	v_mov_b32_e32 v49, s27
	v_cmp_lt_i32_e64 s[36:37], s27, v124
	s_waitcnt lgkmcnt(0)
	s_barrier
	v_cndmask_b32_e64 v48, v48, v49, s[36:37]
	v_sub_u32_e32 v50, v48, v121
	v_lshl_add_u32 v49, v48, 5, v120
	v_lshlrev_b32_e32 v50, 5, v50
	v_cmp_lt_i32_e64 s[38:39], v48, v121
	v_cmp_ge_i32_e64 s[36:37], v48, v121
	s_nop 0
	v_cndmask_b32_e64 v48, v50, v49, s[38:39]
	v_add_u32_e32 v52, v48, v125
	s_and_saveexec_b64 s[28:29], s[36:37]
	s_xor_b64 s[28:29], exec, s[28:29]
	s_cbranch_execz .LBB0_517
	v_ashrrev_i32_e32 v53, 31, v52
	v_lshl_add_u64 v[48:49], v[52:53], 0, v[110:111]
	v_lshlrev_b64 v[48:49], 9, v[48:49]
	v_readlane_b32 s68, v253, 56
	v_lshl_or_b32 v48, v108, 2, v48
	v_readlane_b32 s74, v253, 62
	v_readlane_b32 s75, v253, 63
	v_readlane_b32 s76, v254, 0
	v_readlane_b32 s77, v254, 1
	v_readlane_b32 s69, v253, 57
	v_readlane_b32 s70, v253, 58
	v_readlane_b32 s71, v253, 59
	v_readlane_b32 s72, v253, 60
	v_readlane_b32 s73, v253, 61
	v_readlane_b32 s78, v254, 2
	v_readlane_b32 s79, v254, 3
	v_readlane_b32 s80, v254, 4
	v_readlane_b32 s81, v254, 5
	v_readlane_b32 s82, v254, 6
	v_readlane_b32 s83, v254, 7
	v_lshl_add_u64 v[50:51], s[74:75], 0, v[48:49]
	v_lshl_add_u64 v[48:49], s[76:77], 0, v[48:49]
.LBB0_517:
	s_andn2_saveexec_b64 s[28:29], s[28:29]
	v_add_u32_e32 v48, v52, v118
	v_ashrrev_i32_e32 v49, 31, v48
	v_lshlrev_b64 v[48:49], 13, v[48:49]
	v_lshl_add_u64 v[48:49], v[112:113], 0, v[48:49]
	s_mov_b64 s[16:17], 0x800
	v_lshl_add_u64 v[50:51], v[48:49], 0, s[16:17]
	s_mov_b64 s[16:17], 0xa00
	v_lshl_add_u64 v[48:49], v[48:49], 0, s[16:17]
	s_or_b64 exec, exec, s[28:29]
	v_lshl_add_u64 v[50:51], v[50:51], 0, v[128:129]
	v_mov_b32_e32 v115, v129
	v_mov_b32_e32 v117, v129
	v_lshl_add_u64 v[50:51], v[50:51], 0, v[114:115]
	v_lshl_add_u64 v[52:53], v[48:49], 0, v[116:117]
	global_load_dwordx4 v[60:63], v[50:51], off
	global_load_dwordx4 v[56:59], v[50:51], off offset:64
	s_nop 0
	global_load_dwordx4 v[48:51], v[52:53], off offset:16
	s_nop 0
	global_load_dwordx4 v[52:55], v[52:53], off
	ds_read_b128 v[80:83], v146
	ds_read_b128 v[84:87], v147
	ds_read_b128 v[88:91], v146 offset:2048
	ds_read_b128 v[92:95], v147 offset:2048
	s_waitcnt lgkmcnt(3)
	v_mfma_f32_16x16x32_bf16 v[64:67], v[80:83], v[32:35], 0
	v_add_u32_e32 v68, 0x1000, v148
	ds_read2_b64 v[76:79], v68 offset1:4
	v_xor_b32_e32 v72, 16, v68
	ds_read2_b64 v[72:75], v72 offset0:128 offset1:132
	v_cndmask_b32_e64 v115, v142, v149, s[0:1]
	s_waitcnt lgkmcnt(3)
	v_mfma_f32_16x16x32_bf16 v[96:99], v[88:91], v[32:35], 0
	v_or_b32_e32 v154, v115, v119
	v_sub_u32_e32 v155, v122, v154
	v_sub_u32_e32 v153, v134, v154
	v_mfma_f32_16x16x32_bf16 v[100:103], v[84:87], v[36:39], v[64:67]
	v_sub_u32_e32 v117, v135, v154
	s_nop 1
	v_add_u32_e32 v64, 0x1800, v148
	ds_read2_b64 v[68:71], v64 offset0:4 offset1:0
	v_xor_b32_e32 v66, 16, v64
	ds_read2_b64 v[64:67], v66 offset0:132 offset1:128
	s_waitcnt lgkmcnt(4)
	v_mfma_f32_16x16x32_bf16 v[96:99], v[92:95], v[36:39], v[96:99]
	s_and_saveexec_b64 s[28:29], s[0:1]
	s_cbranch_execz .LBB0_521
	v_sub_u32_e32 v115, 0, v155
	v_max_i32_e32 v115, v155, v115
	s_movk_i32 s16, 0x80
	v_cmp_lt_u32_e64 s[36:37], s16, v115
	v_xad_u32 v115, v154, -1, v122
	v_sub_u32_e32 v156, 0, v115
	v_mov_b32_e32 v157, 0xf149f2ca
	v_max_i32_e32 v115, v115, v156
	s_movk_i32 s16, 0x81
	v_cndmask_b32_e64 v100, v100, v157, s[36:37]
	v_cmp_gt_u32_e64 s[36:37], s16, v115
	v_sub_u32_e32 v115, 0, v153
	v_max_i32_e32 v115, v153, v115
	v_cndmask_b32_e64 v101, v157, v101, s[36:37]
	v_cmp_gt_u32_e64 s[36:37], s16, v115
	v_sub_u32_e32 v115, 0, v117
	v_max_i32_e32 v115, v117, v115
	v_cndmask_b32_e64 v102, v157, v102, s[36:37]
	v_cmp_gt_u32_e64 s[36:37], s16, v115
	v_sub_u32_e32 v115, v136, v154
	v_sub_u32_e32 v156, 0, v115
	v_max_i32_e32 v115, v115, v156
	v_cndmask_b32_e64 v103, v157, v103, s[36:37]
	v_cmp_gt_u32_e64 s[36:37], s16, v115
	v_sub_u32_e32 v115, v137, v154
	v_sub_u32_e32 v156, 0, v115
	v_max_i32_e32 v115, v115, v156
	v_cndmask_b32_e64 v96, v157, v96, s[36:37]
	v_cmp_gt_u32_e64 s[36:37], s16, v115
	v_sub_u32_e32 v115, v138, v154
	v_sub_u32_e32 v156, 0, v115
	v_max_i32_e32 v115, v115, v156
	v_cndmask_b32_e64 v97, v157, v97, s[36:37]
	v_cmp_gt_u32_e64 s[36:37], s16, v115
	v_sub_u32_e32 v115, v139, v154
	v_sub_u32_e32 v156, 0, v115
	v_max_i32_e32 v115, v115, v156
	v_cndmask_b32_e64 v98, v157, v98, s[36:37]
	v_cmp_gt_u32_e64 s[36:37], s16, v115
	s_nop 1
	v_cndmask_b32_e64 v99, v157, v99, s[36:37]
